# P2 part 1 (LoRA-input lerp + tanh|id|sigmoid): branch-free hand-written streaming path (per-lane activation constants)
# speedup vs baseline: 1.0081x; 1.0006x over previous
.LBB0_531:
	s_cmp_lt_i32 s88, 3
	s_cselect_b64 s[4:5], -1, 0
	s_and_b64 s[26:27], s[4:5], s[0:1]
	s_andn2_b64 vcc, exec, s[26:27]
	s_cbranch_vccnz .LBB0_679
	s_mov_b32 s3, 0
	s_and_b32 s22, s87, 0xffffffc0
	s_ashr_i32 s23, s22, 31
	s_ashr_i32 s21, s92, 31
	s_lshl_b64 s[0:1], s[2:3], 9
	s_add_u32 s0, s0, s22
	s_addc_u32 s1, s1, s23
	v_mbcnt_lo_u32_b32 v40, -1, 0
	v_mbcnt_hi_u32_b32 v40, -1, v40
	s_mov_b32 s20, s92
	v_ashrrev_i32_e32 v41, 31, v40
	v_lshl_add_u64 v[44:45], s[0:1], 0, v[40:41]
	s_mov_b64 s[34:35], 0x200000
	s_lshl_b64 s[28:29], s[20:21], 9
	v_lshlrev_b32_e32 v56, 3, v40
	v_cmp_gt_u64_e32 vcc, s[34:35], v[44:45]
	v_lshlrev_b64 v[88:89], 3, v[44:45]
	s_mul_hi_i32 s31, s92, 0x600
	s_mul_i32 s30, s92, 0x600
	s_mul_i32 s74, s92, 0x3000
	s_cmp_eq_u32 s92, 0x100
	s_cbranch_scc0 .Lp2a_compiled
	v_mbcnt_lo_u32_b32 v0, -1, 0
	v_mbcnt_hi_u32_b32 v0, -1, v0
	s_lshl_b32 s4, s2, 3
	s_add_i32 s4, s4, s33
	s_lshl_b32 s4, s4, 5
	v_and_b32_e32 v1, 31, v0
	v_lshrrev_b32_e32 v5, 5, v0
	v_lshlrev_b32_e32 v2, 4, v1
	v_mul_u32_u24_e32 v6, 0xe00, v5
	v_add_u32_e32 v2, v2, v6
	v_lshlrev_b32_e32 v3, 4, v0
	v_lshlrev_b32_e32 v4, 5, v1
	v_add_u32_e32 v4, 0x1800, v4
	global_load_dwordx4 v[8:11], v4, s[46:47]
	global_load_dwordx4 v[12:15], v4, s[46:47] offset:16
	v_cmp_gt_u32_e32 vcc, 8, v1
	v_cmp_lt_u32_e64 s[6:7], 15, v1
	v_mov_b32_e32 v7, 0x4038aa3b
	v_mov_b32_e32 v68, 0xbfb8aa3b
	v_mov_b32_e32 v69, 0
	v_cndmask_b32_e64 v16, v69, v68, s[6:7]
	v_cndmask_b32_e32 v16, v16, v7, vcc
	v_mov_b32_e32 v17, v16
	v_cndmask_b32_e64 v18, 0, 1.0, vcc
	v_mov_b32_e32 v19, v18
	v_cndmask_b32_e64 v20, 0, 1.0, s[6:7]
	v_cndmask_b32_e64 v20, v20, -2.0, vcc
	v_mov_b32_e32 v21, v20
	s_or_b64 s[8:9], vcc, s[6:7]
	v_cndmask_b32_e64 v22, 1.0, 0, s[8:9]
	v_mov_b32_e32 v23, v22
	v_mov_b32_e32 v24, 1.0
	v_mov_b32_e32 v25, 1.0
	s_mul_i32 s5, s4, 0xe00
	s_add_u32 s10, s96, 0xf800c00
	s_addc_u32 s11, s97, 0
	s_add_u32 s10, s10, s5
	s_addc_u32 s11, s11, 0
	s_lshl_b32 s5, s4, 9
	s_add_u32 s12, s96, 0x25800000
	s_addc_u32 s13, s97, 0
	s_add_u32 s12, s12, s5
	s_addc_u32 s13, s13, 0
	s_and_b32 s14, s4, 0x7ff
	s_cmp_eq_u32 s14, 0
	s_cselect_b64 s[14:15], -1, 0
	v_subrev_u32_e32 v6, 0xe00, v2
	s_sub_u32 s16, s10, 0xe00
	s_subb_u32 s17, s11, 0
	global_load_dwordx4 v[100:103], v2, s[10:11]
	v_cmp_gt_u32_e64 s[18:19], 32, v0
	s_and_b64 s[18:19], s[18:19], s[14:15]
	v_add_u32_e32 v6, 0xe00, v2
	v_cndmask_b32_e64 v6, v2, v6, s[18:19]
	global_load_dwordx4 v[104:107], v6, s[16:17]
	s_add_u32 s10, s10, 0x1c00
	s_addc_u32 s11, s11, 0
	s_add_u32 s16, s16, 0x1c00
	s_addc_u32 s17, s17, 0
	global_load_dwordx4 v[108:111], v2, s[10:11]
	global_load_dwordx4 v[112:115], v2, s[16:17]
	s_add_u32 s10, s10, 0x1c00
	s_addc_u32 s11, s11, 0
	s_add_u32 s16, s16, 0x1c00
	s_addc_u32 s17, s17, 0
	global_load_dwordx4 v[116:119], v2, s[10:11]
	global_load_dwordx4 v[120:123], v2, s[16:17]
	s_add_u32 s10, s10, 0x1c00
	s_addc_u32 s11, s11, 0
	s_add_u32 s16, s16, 0x1c00
	s_addc_u32 s17, s17, 0
	global_load_dwordx4 v[124:127], v2, s[10:11]
	global_load_dwordx4 v[128:131], v2, s[16:17]
	s_add_u32 s10, s10, 0x1c00
	s_addc_u32 s11, s11, 0
	s_add_u32 s16, s16, 0x1c00
	s_addc_u32 s17, s17, 0
	global_load_dwordx4 v[132:135], v2, s[10:11]
	global_load_dwordx4 v[136:139], v2, s[16:17]
	s_add_u32 s10, s10, 0x1c00
	s_addc_u32 s11, s11, 0
	s_add_u32 s16, s16, 0x1c00
	s_addc_u32 s17, s17, 0
	global_load_dwordx4 v[140:143], v2, s[10:11]
	global_load_dwordx4 v[144:147], v2, s[16:17]
	s_add_u32 s10, s10, 0x1c00
	s_addc_u32 s11, s11, 0
	s_add_u32 s16, s16, 0x1c00
	s_addc_u32 s17, s17, 0
	global_load_dwordx4 v[148:151], v2, s[10:11]
	global_load_dwordx4 v[152:155], v2, s[16:17]
	s_add_u32 s10, s10, 0x1c00
	s_addc_u32 s11, s11, 0
	s_add_u32 s16, s16, 0x1c00
	s_addc_u32 s17, s17, 0
	global_load_dwordx4 v[156:159], v2, s[10:11]
	global_load_dwordx4 v[160:163], v2, s[16:17]
	s_add_u32 s10, s10, 0x1c00
	s_addc_u32 s11, s11, 0
	s_add_u32 s16, s16, 0x1c00
	s_addc_u32 s17, s17, 0
	global_load_dwordx4 v[164:167], v2, s[10:11]
	global_load_dwordx4 v[168:171], v2, s[16:17]
	s_add_u32 s10, s10, 0x1c00
	s_addc_u32 s11, s11, 0
	s_add_u32 s16, s16, 0x1c00
	s_addc_u32 s17, s17, 0
	global_load_dwordx4 v[172:175], v2, s[10:11]
	global_load_dwordx4 v[176:179], v2, s[16:17]
	s_add_u32 s10, s10, 0x1c00
	s_addc_u32 s11, s11, 0
	s_add_u32 s16, s16, 0x1c00
	s_addc_u32 s17, s17, 0
	global_load_dwordx4 v[180:183], v2, s[10:11]
	global_load_dwordx4 v[184:187], v2, s[16:17]
	s_add_u32 s10, s10, 0x1c00
	s_addc_u32 s11, s11, 0
	s_add_u32 s16, s16, 0x1c00
	s_addc_u32 s17, s17, 0
	global_load_dwordx4 v[188:191], v2, s[10:11]
	global_load_dwordx4 v[192:195], v2, s[16:17]
	s_add_u32 s10, s10, 0x1c00
	s_addc_u32 s11, s11, 0
	s_add_u32 s16, s16, 0x1c00
	s_addc_u32 s17, s17, 0
	global_load_dwordx4 v[196:199], v2, s[10:11]
	global_load_dwordx4 v[200:203], v2, s[16:17]
	s_add_u32 s10, s10, 0x1c00
	s_addc_u32 s11, s11, 0
	s_add_u32 s16, s16, 0x1c00
	s_addc_u32 s17, s17, 0
	global_load_dwordx4 v[204:207], v2, s[10:11]
	global_load_dwordx4 v[208:211], v2, s[16:17]
	s_add_u32 s10, s10, 0x1c00
	s_addc_u32 s11, s11, 0
	s_add_u32 s16, s16, 0x1c00
	s_addc_u32 s17, s17, 0
	global_load_dwordx4 v[212:215], v2, s[10:11]
	global_load_dwordx4 v[216:219], v2, s[16:17]
	s_add_u32 s10, s10, 0x1c00
	s_addc_u32 s11, s11, 0
	s_add_u32 s16, s16, 0x1c00
	s_addc_u32 s17, s17, 0
	global_load_dwordx4 v[220:223], v2, s[10:11]
	global_load_dwordx4 v[224:227], v2, s[16:17]
	s_add_u32 s10, s10, 0x1c00
	s_addc_u32 s11, s11, 0
	s_add_u32 s16, s16, 0x1c00
	s_addc_u32 s17, s17, 0
	s_waitcnt vmcnt(30)
	v_lshlrev_b32_e32 v32, 16, v100
	v_and_b32_e32 v33, 0xffff0000, v100
	v_lshlrev_b32_e32 v34, 16, v101
	v_and_b32_e32 v35, 0xffff0000, v101
	v_lshlrev_b32_e32 v36, 16, v102
	v_and_b32_e32 v37, 0xffff0000, v102
	v_lshlrev_b32_e32 v38, 16, v103
	v_and_b32_e32 v39, 0xffff0000, v103
	v_lshlrev_b32_e32 v40, 16, v104
	v_and_b32_e32 v41, 0xffff0000, v104
	v_lshlrev_b32_e32 v42, 16, v105
	v_and_b32_e32 v43, 0xffff0000, v105
	v_lshlrev_b32_e32 v44, 16, v106
	v_and_b32_e32 v45, 0xffff0000, v106
	v_lshlrev_b32_e32 v46, 16, v107
	v_and_b32_e32 v47, 0xffff0000, v107
	v_cndmask_b32_e64 v40, v40, 0, s[18:19]
	v_cndmask_b32_e64 v41, v41, 0, s[18:19]
	v_cndmask_b32_e64 v42, v42, 0, s[18:19]
	v_cndmask_b32_e64 v43, v43, 0, s[18:19]
	v_cndmask_b32_e64 v44, v44, 0, s[18:19]
	v_cndmask_b32_e64 v45, v45, 0, s[18:19]
	v_cndmask_b32_e64 v46, v46, 0, s[18:19]
	v_cndmask_b32_e64 v47, v47, 0, s[18:19]
	v_pk_add_f32 v[40:41], v[40:41], v[32:33] neg_lo:[0,1] neg_hi:[0,1]
	v_pk_add_f32 v[42:43], v[42:43], v[34:35] neg_lo:[0,1] neg_hi:[0,1]
	v_pk_add_f32 v[44:45], v[44:45], v[36:37] neg_lo:[0,1] neg_hi:[0,1]
	v_pk_add_f32 v[46:47], v[46:47], v[38:39] neg_lo:[0,1] neg_hi:[0,1]
	v_pk_fma_f32 v[48:49], v[40:41], v[8:9], v[32:33]
	v_pk_fma_f32 v[50:51], v[42:43], v[10:11], v[34:35]
	v_pk_fma_f32 v[52:53], v[44:45], v[12:13], v[36:37]
	v_pk_fma_f32 v[54:55], v[46:47], v[14:15], v[38:39]
	v_pk_mul_f32 v[56:57], v[48:49], v[16:17]
	v_pk_mul_f32 v[58:59], v[50:51], v[16:17]
	v_pk_mul_f32 v[60:61], v[52:53], v[16:17]
	v_pk_mul_f32 v[62:63], v[54:55], v[16:17]
	v_exp_f32_e32 v56, v56
	v_exp_f32_e32 v57, v57
	v_exp_f32_e32 v58, v58
	v_exp_f32_e32 v59, v59
	v_exp_f32_e32 v60, v60
	v_exp_f32_e32 v61, v61
	v_exp_f32_e32 v62, v62
	v_exp_f32_e32 v63, v63
	s_nop 0
	v_pk_add_f32 v[56:57], v[56:57], v[24:25]
	v_pk_add_f32 v[58:59], v[58:59], v[24:25]
	v_pk_add_f32 v[60:61], v[60:61], v[24:25]
	v_pk_add_f32 v[62:63], v[62:63], v[24:25]
	v_rcp_f32_e32 v56, v56
	v_rcp_f32_e32 v57, v57
	v_rcp_f32_e32 v58, v58
	v_rcp_f32_e32 v59, v59
	v_rcp_f32_e32 v60, v60
	v_rcp_f32_e32 v61, v61
	v_rcp_f32_e32 v62, v62
	v_rcp_f32_e32 v63, v63
	s_nop 0
	v_pk_fma_f32 v[56:57], v[56:57], v[20:21], v[18:19]
	v_pk_fma_f32 v[58:59], v[58:59], v[20:21], v[18:19]
	v_pk_fma_f32 v[60:61], v[60:61], v[20:21], v[18:19]
	v_pk_fma_f32 v[62:63], v[62:63], v[20:21], v[18:19]
	v_pk_fma_f32 v[56:57], v[48:49], v[22:23], v[56:57]
	v_pk_fma_f32 v[58:59], v[50:51], v[22:23], v[58:59]
	v_pk_fma_f32 v[60:61], v[52:53], v[22:23], v[60:61]
	v_pk_fma_f32 v[62:63], v[54:55], v[22:23], v[62:63]
	v_cvt_pk_bf16_f32 v64, v56, v57
	v_cvt_pk_bf16_f32 v65, v58, v59
	v_cvt_pk_bf16_f32 v66, v60, v61
	v_cvt_pk_bf16_f32 v67, v62, v63
	global_store_dwordx4 v3, v[64:67], s[12:13]
	s_add_u32 s12, s12, 0x400
	s_addc_u32 s13, s13, 0
	s_waitcnt vmcnt(29)
	v_lshlrev_b32_e32 v32, 16, v108
	v_and_b32_e32 v33, 0xffff0000, v108
	v_lshlrev_b32_e32 v34, 16, v109
	v_and_b32_e32 v35, 0xffff0000, v109
	v_lshlrev_b32_e32 v36, 16, v110
	v_and_b32_e32 v37, 0xffff0000, v110
	v_lshlrev_b32_e32 v38, 16, v111
	v_and_b32_e32 v39, 0xffff0000, v111
	v_lshlrev_b32_e32 v40, 16, v112
	v_and_b32_e32 v41, 0xffff0000, v112
	v_lshlrev_b32_e32 v42, 16, v113
	v_and_b32_e32 v43, 0xffff0000, v113
	v_lshlrev_b32_e32 v44, 16, v114
	v_and_b32_e32 v45, 0xffff0000, v114
	v_lshlrev_b32_e32 v46, 16, v115
	v_and_b32_e32 v47, 0xffff0000, v115
	v_pk_add_f32 v[40:41], v[40:41], v[32:33] neg_lo:[0,1] neg_hi:[0,1]
	v_pk_add_f32 v[42:43], v[42:43], v[34:35] neg_lo:[0,1] neg_hi:[0,1]
	v_pk_add_f32 v[44:45], v[44:45], v[36:37] neg_lo:[0,1] neg_hi:[0,1]
	v_pk_add_f32 v[46:47], v[46:47], v[38:39] neg_lo:[0,1] neg_hi:[0,1]
	v_pk_fma_f32 v[48:49], v[40:41], v[8:9], v[32:33]
	v_pk_fma_f32 v[50:51], v[42:43], v[10:11], v[34:35]
	v_pk_fma_f32 v[52:53], v[44:45], v[12:13], v[36:37]
	v_pk_fma_f32 v[54:55], v[46:47], v[14:15], v[38:39]
	v_pk_mul_f32 v[56:57], v[48:49], v[16:17]
	v_pk_mul_f32 v[58:59], v[50:51], v[16:17]
	v_pk_mul_f32 v[60:61], v[52:53], v[16:17]
	v_pk_mul_f32 v[62:63], v[54:55], v[16:17]
	v_exp_f32_e32 v56, v56
	v_exp_f32_e32 v57, v57
	v_exp_f32_e32 v58, v58
	v_exp_f32_e32 v59, v59
	v_exp_f32_e32 v60, v60
	v_exp_f32_e32 v61, v61
	v_exp_f32_e32 v62, v62
	v_exp_f32_e32 v63, v63
	s_nop 0
	v_pk_add_f32 v[56:57], v[56:57], v[24:25]
	v_pk_add_f32 v[58:59], v[58:59], v[24:25]
	v_pk_add_f32 v[60:61], v[60:61], v[24:25]
	v_pk_add_f32 v[62:63], v[62:63], v[24:25]
	v_rcp_f32_e32 v56, v56
	v_rcp_f32_e32 v57, v57
	v_rcp_f32_e32 v58, v58
	v_rcp_f32_e32 v59, v59
	v_rcp_f32_e32 v60, v60
	v_rcp_f32_e32 v61, v61
	v_rcp_f32_e32 v62, v62
	v_rcp_f32_e32 v63, v63
	s_nop 0
	v_pk_fma_f32 v[56:57], v[56:57], v[20:21], v[18:19]
	v_pk_fma_f32 v[58:59], v[58:59], v[20:21], v[18:19]
	v_pk_fma_f32 v[60:61], v[60:61], v[20:21], v[18:19]
	v_pk_fma_f32 v[62:63], v[62:63], v[20:21], v[18:19]
	v_pk_fma_f32 v[56:57], v[48:49], v[22:23], v[56:57]
	v_pk_fma_f32 v[58:59], v[50:51], v[22:23], v[58:59]
	v_pk_fma_f32 v[60:61], v[52:53], v[22:23], v[60:61]
	v_pk_fma_f32 v[62:63], v[54:55], v[22:23], v[62:63]
	v_cvt_pk_bf16_f32 v64, v56, v57
	v_cvt_pk_bf16_f32 v65, v58, v59
	v_cvt_pk_bf16_f32 v66, v60, v61
	v_cvt_pk_bf16_f32 v67, v62, v63
	global_store_dwordx4 v3, v[64:67], s[12:13]
	s_add_u32 s12, s12, 0x400
	s_addc_u32 s13, s13, 0
	s_waitcnt vmcnt(28)
	v_lshlrev_b32_e32 v32, 16, v116
	v_and_b32_e32 v33, 0xffff0000, v116
	v_lshlrev_b32_e32 v34, 16, v117
	v_and_b32_e32 v35, 0xffff0000, v117
	v_lshlrev_b32_e32 v36, 16, v118
	v_and_b32_e32 v37, 0xffff0000, v118
	v_lshlrev_b32_e32 v38, 16, v119
	v_and_b32_e32 v39, 0xffff0000, v119
	v_lshlrev_b32_e32 v40, 16, v120
	v_and_b32_e32 v41, 0xffff0000, v120
	v_lshlrev_b32_e32 v42, 16, v121
	v_and_b32_e32 v43, 0xffff0000, v121
	v_lshlrev_b32_e32 v44, 16, v122
	v_and_b32_e32 v45, 0xffff0000, v122
	v_lshlrev_b32_e32 v46, 16, v123
	v_and_b32_e32 v47, 0xffff0000, v123
	v_pk_add_f32 v[40:41], v[40:41], v[32:33] neg_lo:[0,1] neg_hi:[0,1]
	v_pk_add_f32 v[42:43], v[42:43], v[34:35] neg_lo:[0,1] neg_hi:[0,1]
	v_pk_add_f32 v[44:45], v[44:45], v[36:37] neg_lo:[0,1] neg_hi:[0,1]
	v_pk_add_f32 v[46:47], v[46:47], v[38:39] neg_lo:[0,1] neg_hi:[0,1]
	v_pk_fma_f32 v[48:49], v[40:41], v[8:9], v[32:33]
	v_pk_fma_f32 v[50:51], v[42:43], v[10:11], v[34:35]
	v_pk_fma_f32 v[52:53], v[44:45], v[12:13], v[36:37]
	v_pk_fma_f32 v[54:55], v[46:47], v[14:15], v[38:39]
	v_pk_mul_f32 v[56:57], v[48:49], v[16:17]
	v_pk_mul_f32 v[58:59], v[50:51], v[16:17]
	v_pk_mul_f32 v[60:61], v[52:53], v[16:17]
	v_pk_mul_f32 v[62:63], v[54:55], v[16:17]
	v_exp_f32_e32 v56, v56
	v_exp_f32_e32 v57, v57
	v_exp_f32_e32 v58, v58
	v_exp_f32_e32 v59, v59
	v_exp_f32_e32 v60, v60
	v_exp_f32_e32 v61, v61
	v_exp_f32_e32 v62, v62
	v_exp_f32_e32 v63, v63
	s_nop 0
	v_pk_add_f32 v[56:57], v[56:57], v[24:25]
	v_pk_add_f32 v[58:59], v[58:59], v[24:25]
	v_pk_add_f32 v[60:61], v[60:61], v[24:25]
	v_pk_add_f32 v[62:63], v[62:63], v[24:25]
	v_rcp_f32_e32 v56, v56
	v_rcp_f32_e32 v57, v57
	v_rcp_f32_e32 v58, v58
	v_rcp_f32_e32 v59, v59
	v_rcp_f32_e32 v60, v60
	v_rcp_f32_e32 v61, v61
	v_rcp_f32_e32 v62, v62
	v_rcp_f32_e32 v63, v63
	s_nop 0
	v_pk_fma_f32 v[56:57], v[56:57], v[20:21], v[18:19]
	v_pk_fma_f32 v[58:59], v[58:59], v[20:21], v[18:19]
	v_pk_fma_f32 v[60:61], v[60:61], v[20:21], v[18:19]
	v_pk_fma_f32 v[62:63], v[62:63], v[20:21], v[18:19]
	v_pk_fma_f32 v[56:57], v[48:49], v[22:23], v[56:57]
	v_pk_fma_f32 v[58:59], v[50:51], v[22:23], v[58:59]
	v_pk_fma_f32 v[60:61], v[52:53], v[22:23], v[60:61]
	v_pk_fma_f32 v[62:63], v[54:55], v[22:23], v[62:63]
	v_cvt_pk_bf16_f32 v64, v56, v57
	v_cvt_pk_bf16_f32 v65, v58, v59
	v_cvt_pk_bf16_f32 v66, v60, v61
	v_cvt_pk_bf16_f32 v67, v62, v63
	global_store_dwordx4 v3, v[64:67], s[12:13]
	s_add_u32 s12, s12, 0x400
	s_addc_u32 s13, s13, 0
	s_waitcnt vmcnt(27)
	v_lshlrev_b32_e32 v32, 16, v124
	v_and_b32_e32 v33, 0xffff0000, v124
	v_lshlrev_b32_e32 v34, 16, v125
	v_and_b32_e32 v35, 0xffff0000, v125
	v_lshlrev_b32_e32 v36, 16, v126
	v_and_b32_e32 v37, 0xffff0000, v126
	v_lshlrev_b32_e32 v38, 16, v127
	v_and_b32_e32 v39, 0xffff0000, v127
	v_lshlrev_b32_e32 v40, 16, v128
	v_and_b32_e32 v41, 0xffff0000, v128
	v_lshlrev_b32_e32 v42, 16, v129
	v_and_b32_e32 v43, 0xffff0000, v129
	v_lshlrev_b32_e32 v44, 16, v130
	v_and_b32_e32 v45, 0xffff0000, v130
	v_lshlrev_b32_e32 v46, 16, v131
	v_and_b32_e32 v47, 0xffff0000, v131
	v_pk_add_f32 v[40:41], v[40:41], v[32:33] neg_lo:[0,1] neg_hi:[0,1]
	v_pk_add_f32 v[42:43], v[42:43], v[34:35] neg_lo:[0,1] neg_hi:[0,1]
	v_pk_add_f32 v[44:45], v[44:45], v[36:37] neg_lo:[0,1] neg_hi:[0,1]
	v_pk_add_f32 v[46:47], v[46:47], v[38:39] neg_lo:[0,1] neg_hi:[0,1]
	v_pk_fma_f32 v[48:49], v[40:41], v[8:9], v[32:33]
	v_pk_fma_f32 v[50:51], v[42:43], v[10:11], v[34:35]
	v_pk_fma_f32 v[52:53], v[44:45], v[12:13], v[36:37]
	v_pk_fma_f32 v[54:55], v[46:47], v[14:15], v[38:39]
	v_pk_mul_f32 v[56:57], v[48:49], v[16:17]
	v_pk_mul_f32 v[58:59], v[50:51], v[16:17]
	v_pk_mul_f32 v[60:61], v[52:53], v[16:17]
	v_pk_mul_f32 v[62:63], v[54:55], v[16:17]
	v_exp_f32_e32 v56, v56
	v_exp_f32_e32 v57, v57
	v_exp_f32_e32 v58, v58
	v_exp_f32_e32 v59, v59
	v_exp_f32_e32 v60, v60
	v_exp_f32_e32 v61, v61
	v_exp_f32_e32 v62, v62
	v_exp_f32_e32 v63, v63
	s_nop 0
	v_pk_add_f32 v[56:57], v[56:57], v[24:25]
	v_pk_add_f32 v[58:59], v[58:59], v[24:25]
	v_pk_add_f32 v[60:61], v[60:61], v[24:25]
	v_pk_add_f32 v[62:63], v[62:63], v[24:25]
	v_rcp_f32_e32 v56, v56
	v_rcp_f32_e32 v57, v57
	v_rcp_f32_e32 v58, v58
	v_rcp_f32_e32 v59, v59
	v_rcp_f32_e32 v60, v60
	v_rcp_f32_e32 v61, v61
	v_rcp_f32_e32 v62, v62
	v_rcp_f32_e32 v63, v63
	s_nop 0
	v_pk_fma_f32 v[56:57], v[56:57], v[20:21], v[18:19]
	v_pk_fma_f32 v[58:59], v[58:59], v[20:21], v[18:19]
	v_pk_fma_f32 v[60:61], v[60:61], v[20:21], v[18:19]
	v_pk_fma_f32 v[62:63], v[62:63], v[20:21], v[18:19]
	v_pk_fma_f32 v[56:57], v[48:49], v[22:23], v[56:57]
	v_pk_fma_f32 v[58:59], v[50:51], v[22:23], v[58:59]
	v_pk_fma_f32 v[60:61], v[52:53], v[22:23], v[60:61]
	v_pk_fma_f32 v[62:63], v[54:55], v[22:23], v[62:63]
	v_cvt_pk_bf16_f32 v64, v56, v57
	v_cvt_pk_bf16_f32 v65, v58, v59
	v_cvt_pk_bf16_f32 v66, v60, v61
	v_cvt_pk_bf16_f32 v67, v62, v63
	global_store_dwordx4 v3, v[64:67], s[12:13]
	s_add_u32 s12, s12, 0x400
	s_addc_u32 s13, s13, 0
	s_waitcnt vmcnt(26)
	v_lshlrev_b32_e32 v32, 16, v132
	v_and_b32_e32 v33, 0xffff0000, v132
	v_lshlrev_b32_e32 v34, 16, v133
	v_and_b32_e32 v35, 0xffff0000, v133
	v_lshlrev_b32_e32 v36, 16, v134
	v_and_b32_e32 v37, 0xffff0000, v134
	v_lshlrev_b32_e32 v38, 16, v135
	v_and_b32_e32 v39, 0xffff0000, v135
	v_lshlrev_b32_e32 v40, 16, v136
	v_and_b32_e32 v41, 0xffff0000, v136
	v_lshlrev_b32_e32 v42, 16, v137
	v_and_b32_e32 v43, 0xffff0000, v137
	v_lshlrev_b32_e32 v44, 16, v138
	v_and_b32_e32 v45, 0xffff0000, v138
	v_lshlrev_b32_e32 v46, 16, v139
	v_and_b32_e32 v47, 0xffff0000, v139
	v_pk_add_f32 v[40:41], v[40:41], v[32:33] neg_lo:[0,1] neg_hi:[0,1]
	v_pk_add_f32 v[42:43], v[42:43], v[34:35] neg_lo:[0,1] neg_hi:[0,1]
	v_pk_add_f32 v[44:45], v[44:45], v[36:37] neg_lo:[0,1] neg_hi:[0,1]
	v_pk_add_f32 v[46:47], v[46:47], v[38:39] neg_lo:[0,1] neg_hi:[0,1]
	v_pk_fma_f32 v[48:49], v[40:41], v[8:9], v[32:33]
	v_pk_fma_f32 v[50:51], v[42:43], v[10:11], v[34:35]
	v_pk_fma_f32 v[52:53], v[44:45], v[12:13], v[36:37]
	v_pk_fma_f32 v[54:55], v[46:47], v[14:15], v[38:39]
	v_pk_mul_f32 v[56:57], v[48:49], v[16:17]
	v_pk_mul_f32 v[58:59], v[50:51], v[16:17]
	v_pk_mul_f32 v[60:61], v[52:53], v[16:17]
	v_pk_mul_f32 v[62:63], v[54:55], v[16:17]
	v_exp_f32_e32 v56, v56
	v_exp_f32_e32 v57, v57
	v_exp_f32_e32 v58, v58
	v_exp_f32_e32 v59, v59
	v_exp_f32_e32 v60, v60
	v_exp_f32_e32 v61, v61
	v_exp_f32_e32 v62, v62
	v_exp_f32_e32 v63, v63
	s_nop 0
	v_pk_add_f32 v[56:57], v[56:57], v[24:25]
	v_pk_add_f32 v[58:59], v[58:59], v[24:25]
	v_pk_add_f32 v[60:61], v[60:61], v[24:25]
	v_pk_add_f32 v[62:63], v[62:63], v[24:25]
	v_rcp_f32_e32 v56, v56
	v_rcp_f32_e32 v57, v57
	v_rcp_f32_e32 v58, v58
	v_rcp_f32_e32 v59, v59
	v_rcp_f32_e32 v60, v60
	v_rcp_f32_e32 v61, v61
	v_rcp_f32_e32 v62, v62
	v_rcp_f32_e32 v63, v63
	s_nop 0
	v_pk_fma_f32 v[56:57], v[56:57], v[20:21], v[18:19]
	v_pk_fma_f32 v[58:59], v[58:59], v[20:21], v[18:19]
	v_pk_fma_f32 v[60:61], v[60:61], v[20:21], v[18:19]
	v_pk_fma_f32 v[62:63], v[62:63], v[20:21], v[18:19]
	v_pk_fma_f32 v[56:57], v[48:49], v[22:23], v[56:57]
	v_pk_fma_f32 v[58:59], v[50:51], v[22:23], v[58:59]
	v_pk_fma_f32 v[60:61], v[52:53], v[22:23], v[60:61]
	v_pk_fma_f32 v[62:63], v[54:55], v[22:23], v[62:63]
	v_cvt_pk_bf16_f32 v64, v56, v57
	v_cvt_pk_bf16_f32 v65, v58, v59
	v_cvt_pk_bf16_f32 v66, v60, v61
	v_cvt_pk_bf16_f32 v67, v62, v63
	global_store_dwordx4 v3, v[64:67], s[12:13]
	s_add_u32 s12, s12, 0x400
	s_addc_u32 s13, s13, 0
	s_waitcnt vmcnt(25)
	v_lshlrev_b32_e32 v32, 16, v140
	v_and_b32_e32 v33, 0xffff0000, v140
	v_lshlrev_b32_e32 v34, 16, v141
	v_and_b32_e32 v35, 0xffff0000, v141
	v_lshlrev_b32_e32 v36, 16, v142
	v_and_b32_e32 v37, 0xffff0000, v142
	v_lshlrev_b32_e32 v38, 16, v143
	v_and_b32_e32 v39, 0xffff0000, v143
	v_lshlrev_b32_e32 v40, 16, v144
	v_and_b32_e32 v41, 0xffff0000, v144
	v_lshlrev_b32_e32 v42, 16, v145
	v_and_b32_e32 v43, 0xffff0000, v145
	v_lshlrev_b32_e32 v44, 16, v146
	v_and_b32_e32 v45, 0xffff0000, v146
	v_lshlrev_b32_e32 v46, 16, v147
	v_and_b32_e32 v47, 0xffff0000, v147
	v_pk_add_f32 v[40:41], v[40:41], v[32:33] neg_lo:[0,1] neg_hi:[0,1]
	v_pk_add_f32 v[42:43], v[42:43], v[34:35] neg_lo:[0,1] neg_hi:[0,1]
	v_pk_add_f32 v[44:45], v[44:45], v[36:37] neg_lo:[0,1] neg_hi:[0,1]
	v_pk_add_f32 v[46:47], v[46:47], v[38:39] neg_lo:[0,1] neg_hi:[0,1]
	v_pk_fma_f32 v[48:49], v[40:41], v[8:9], v[32:33]
	v_pk_fma_f32 v[50:51], v[42:43], v[10:11], v[34:35]
	v_pk_fma_f32 v[52:53], v[44:45], v[12:13], v[36:37]
	v_pk_fma_f32 v[54:55], v[46:47], v[14:15], v[38:39]
	v_pk_mul_f32 v[56:57], v[48:49], v[16:17]
	v_pk_mul_f32 v[58:59], v[50:51], v[16:17]
	v_pk_mul_f32 v[60:61], v[52:53], v[16:17]
	v_pk_mul_f32 v[62:63], v[54:55], v[16:17]
	v_exp_f32_e32 v56, v56
	v_exp_f32_e32 v57, v57
	v_exp_f32_e32 v58, v58
	v_exp_f32_e32 v59, v59
	v_exp_f32_e32 v60, v60
	v_exp_f32_e32 v61, v61
	v_exp_f32_e32 v62, v62
	v_exp_f32_e32 v63, v63
	s_nop 0
	v_pk_add_f32 v[56:57], v[56:57], v[24:25]
	v_pk_add_f32 v[58:59], v[58:59], v[24:25]
	v_pk_add_f32 v[60:61], v[60:61], v[24:25]
	v_pk_add_f32 v[62:63], v[62:63], v[24:25]
	v_rcp_f32_e32 v56, v56
	v_rcp_f32_e32 v57, v57
	v_rcp_f32_e32 v58, v58
	v_rcp_f32_e32 v59, v59
	v_rcp_f32_e32 v60, v60
	v_rcp_f32_e32 v61, v61
	v_rcp_f32_e32 v62, v62
	v_rcp_f32_e32 v63, v63
	s_nop 0
	v_pk_fma_f32 v[56:57], v[56:57], v[20:21], v[18:19]
	v_pk_fma_f32 v[58:59], v[58:59], v[20:21], v[18:19]
	v_pk_fma_f32 v[60:61], v[60:61], v[20:21], v[18:19]
	v_pk_fma_f32 v[62:63], v[62:63], v[20:21], v[18:19]
	v_pk_fma_f32 v[56:57], v[48:49], v[22:23], v[56:57]
	v_pk_fma_f32 v[58:59], v[50:51], v[22:23], v[58:59]
	v_pk_fma_f32 v[60:61], v[52:53], v[22:23], v[60:61]
	v_pk_fma_f32 v[62:63], v[54:55], v[22:23], v[62:63]
	v_cvt_pk_bf16_f32 v64, v56, v57
	v_cvt_pk_bf16_f32 v65, v58, v59
	v_cvt_pk_bf16_f32 v66, v60, v61
	v_cvt_pk_bf16_f32 v67, v62, v63
	global_store_dwordx4 v3, v[64:67], s[12:13]
	s_add_u32 s12, s12, 0x400
	s_addc_u32 s13, s13, 0
	s_waitcnt vmcnt(24)
	v_lshlrev_b32_e32 v32, 16, v148
	v_and_b32_e32 v33, 0xffff0000, v148
	v_lshlrev_b32_e32 v34, 16, v149
	v_and_b32_e32 v35, 0xffff0000, v149
	v_lshlrev_b32_e32 v36, 16, v150
	v_and_b32_e32 v37, 0xffff0000, v150
	v_lshlrev_b32_e32 v38, 16, v151
	v_and_b32_e32 v39, 0xffff0000, v151
	v_lshlrev_b32_e32 v40, 16, v152
	v_and_b32_e32 v41, 0xffff0000, v152
	v_lshlrev_b32_e32 v42, 16, v153
	v_and_b32_e32 v43, 0xffff0000, v153
	v_lshlrev_b32_e32 v44, 16, v154
	v_and_b32_e32 v45, 0xffff0000, v154
	v_lshlrev_b32_e32 v46, 16, v155
	v_and_b32_e32 v47, 0xffff0000, v155
	v_pk_add_f32 v[40:41], v[40:41], v[32:33] neg_lo:[0,1] neg_hi:[0,1]
	v_pk_add_f32 v[42:43], v[42:43], v[34:35] neg_lo:[0,1] neg_hi:[0,1]
	v_pk_add_f32 v[44:45], v[44:45], v[36:37] neg_lo:[0,1] neg_hi:[0,1]
	v_pk_add_f32 v[46:47], v[46:47], v[38:39] neg_lo:[0,1] neg_hi:[0,1]
	v_pk_fma_f32 v[48:49], v[40:41], v[8:9], v[32:33]
	v_pk_fma_f32 v[50:51], v[42:43], v[10:11], v[34:35]
	v_pk_fma_f32 v[52:53], v[44:45], v[12:13], v[36:37]
	v_pk_fma_f32 v[54:55], v[46:47], v[14:15], v[38:39]
	v_pk_mul_f32 v[56:57], v[48:49], v[16:17]
	v_pk_mul_f32 v[58:59], v[50:51], v[16:17]
	v_pk_mul_f32 v[60:61], v[52:53], v[16:17]
	v_pk_mul_f32 v[62:63], v[54:55], v[16:17]
	v_exp_f32_e32 v56, v56
	v_exp_f32_e32 v57, v57
	v_exp_f32_e32 v58, v58
	v_exp_f32_e32 v59, v59
	v_exp_f32_e32 v60, v60
	v_exp_f32_e32 v61, v61
	v_exp_f32_e32 v62, v62
	v_exp_f32_e32 v63, v63
	s_nop 0
	v_pk_add_f32 v[56:57], v[56:57], v[24:25]
	v_pk_add_f32 v[58:59], v[58:59], v[24:25]
	v_pk_add_f32 v[60:61], v[60:61], v[24:25]
	v_pk_add_f32 v[62:63], v[62:63], v[24:25]
	v_rcp_f32_e32 v56, v56
	v_rcp_f32_e32 v57, v57
	v_rcp_f32_e32 v58, v58
	v_rcp_f32_e32 v59, v59
	v_rcp_f32_e32 v60, v60
	v_rcp_f32_e32 v61, v61
	v_rcp_f32_e32 v62, v62
	v_rcp_f32_e32 v63, v63
	s_nop 0
	v_pk_fma_f32 v[56:57], v[56:57], v[20:21], v[18:19]
	v_pk_fma_f32 v[58:59], v[58:59], v[20:21], v[18:19]
	v_pk_fma_f32 v[60:61], v[60:61], v[20:21], v[18:19]
	v_pk_fma_f32 v[62:63], v[62:63], v[20:21], v[18:19]
	v_pk_fma_f32 v[56:57], v[48:49], v[22:23], v[56:57]
	v_pk_fma_f32 v[58:59], v[50:51], v[22:23], v[58:59]
	v_pk_fma_f32 v[60:61], v[52:53], v[22:23], v[60:61]
	v_pk_fma_f32 v[62:63], v[54:55], v[22:23], v[62:63]
	v_cvt_pk_bf16_f32 v64, v56, v57
	v_cvt_pk_bf16_f32 v65, v58, v59
	v_cvt_pk_bf16_f32 v66, v60, v61
	v_cvt_pk_bf16_f32 v67, v62, v63
	global_store_dwordx4 v3, v[64:67], s[12:13]
	s_add_u32 s12, s12, 0x400
	s_addc_u32 s13, s13, 0
	s_waitcnt vmcnt(23)
	v_lshlrev_b32_e32 v32, 16, v156
	v_and_b32_e32 v33, 0xffff0000, v156
	v_lshlrev_b32_e32 v34, 16, v157
	v_and_b32_e32 v35, 0xffff0000, v157
	v_lshlrev_b32_e32 v36, 16, v158
	v_and_b32_e32 v37, 0xffff0000, v158
	v_lshlrev_b32_e32 v38, 16, v159
	v_and_b32_e32 v39, 0xffff0000, v159
	v_lshlrev_b32_e32 v40, 16, v160
	v_and_b32_e32 v41, 0xffff0000, v160
	v_lshlrev_b32_e32 v42, 16, v161
	v_and_b32_e32 v43, 0xffff0000, v161
	v_lshlrev_b32_e32 v44, 16, v162
	v_and_b32_e32 v45, 0xffff0000, v162
	v_lshlrev_b32_e32 v46, 16, v163
	v_and_b32_e32 v47, 0xffff0000, v163
	v_pk_add_f32 v[40:41], v[40:41], v[32:33] neg_lo:[0,1] neg_hi:[0,1]
	v_pk_add_f32 v[42:43], v[42:43], v[34:35] neg_lo:[0,1] neg_hi:[0,1]
	v_pk_add_f32 v[44:45], v[44:45], v[36:37] neg_lo:[0,1] neg_hi:[0,1]
	v_pk_add_f32 v[46:47], v[46:47], v[38:39] neg_lo:[0,1] neg_hi:[0,1]
	v_pk_fma_f32 v[48:49], v[40:41], v[8:9], v[32:33]
	v_pk_fma_f32 v[50:51], v[42:43], v[10:11], v[34:35]
	v_pk_fma_f32 v[52:53], v[44:45], v[12:13], v[36:37]
	v_pk_fma_f32 v[54:55], v[46:47], v[14:15], v[38:39]
	v_pk_mul_f32 v[56:57], v[48:49], v[16:17]
	v_pk_mul_f32 v[58:59], v[50:51], v[16:17]
	v_pk_mul_f32 v[60:61], v[52:53], v[16:17]
	v_pk_mul_f32 v[62:63], v[54:55], v[16:17]
	v_exp_f32_e32 v56, v56
	v_exp_f32_e32 v57, v57
	v_exp_f32_e32 v58, v58
	v_exp_f32_e32 v59, v59
	v_exp_f32_e32 v60, v60
	v_exp_f32_e32 v61, v61
	v_exp_f32_e32 v62, v62
	v_exp_f32_e32 v63, v63
	s_nop 0
	v_pk_add_f32 v[56:57], v[56:57], v[24:25]
	v_pk_add_f32 v[58:59], v[58:59], v[24:25]
	v_pk_add_f32 v[60:61], v[60:61], v[24:25]
	v_pk_add_f32 v[62:63], v[62:63], v[24:25]
	v_rcp_f32_e32 v56, v56
	v_rcp_f32_e32 v57, v57
	v_rcp_f32_e32 v58, v58
	v_rcp_f32_e32 v59, v59
	v_rcp_f32_e32 v60, v60
	v_rcp_f32_e32 v61, v61
	v_rcp_f32_e32 v62, v62
	v_rcp_f32_e32 v63, v63
	s_nop 0
	v_pk_fma_f32 v[56:57], v[56:57], v[20:21], v[18:19]
	v_pk_fma_f32 v[58:59], v[58:59], v[20:21], v[18:19]
	v_pk_fma_f32 v[60:61], v[60:61], v[20:21], v[18:19]
	v_pk_fma_f32 v[62:63], v[62:63], v[20:21], v[18:19]
	v_pk_fma_f32 v[56:57], v[48:49], v[22:23], v[56:57]
	v_pk_fma_f32 v[58:59], v[50:51], v[22:23], v[58:59]
	v_pk_fma_f32 v[60:61], v[52:53], v[22:23], v[60:61]
	v_pk_fma_f32 v[62:63], v[54:55], v[22:23], v[62:63]
	v_cvt_pk_bf16_f32 v64, v56, v57
	v_cvt_pk_bf16_f32 v65, v58, v59
	v_cvt_pk_bf16_f32 v66, v60, v61
	v_cvt_pk_bf16_f32 v67, v62, v63
	global_store_dwordx4 v3, v[64:67], s[12:13]
	s_add_u32 s12, s12, 0x400
	s_addc_u32 s13, s13, 0
	s_waitcnt vmcnt(22)
	v_lshlrev_b32_e32 v32, 16, v164
	v_and_b32_e32 v33, 0xffff0000, v164
	v_lshlrev_b32_e32 v34, 16, v165
	v_and_b32_e32 v35, 0xffff0000, v165
	v_lshlrev_b32_e32 v36, 16, v166
	v_and_b32_e32 v37, 0xffff0000, v166
	v_lshlrev_b32_e32 v38, 16, v167
	v_and_b32_e32 v39, 0xffff0000, v167
	v_lshlrev_b32_e32 v40, 16, v168
	v_and_b32_e32 v41, 0xffff0000, v168
	v_lshlrev_b32_e32 v42, 16, v169
	v_and_b32_e32 v43, 0xffff0000, v169
	v_lshlrev_b32_e32 v44, 16, v170
	v_and_b32_e32 v45, 0xffff0000, v170
	v_lshlrev_b32_e32 v46, 16, v171
	v_and_b32_e32 v47, 0xffff0000, v171
	v_pk_add_f32 v[40:41], v[40:41], v[32:33] neg_lo:[0,1] neg_hi:[0,1]
	v_pk_add_f32 v[42:43], v[42:43], v[34:35] neg_lo:[0,1] neg_hi:[0,1]
	v_pk_add_f32 v[44:45], v[44:45], v[36:37] neg_lo:[0,1] neg_hi:[0,1]
	v_pk_add_f32 v[46:47], v[46:47], v[38:39] neg_lo:[0,1] neg_hi:[0,1]
	v_pk_fma_f32 v[48:49], v[40:41], v[8:9], v[32:33]
	v_pk_fma_f32 v[50:51], v[42:43], v[10:11], v[34:35]
	v_pk_fma_f32 v[52:53], v[44:45], v[12:13], v[36:37]
	v_pk_fma_f32 v[54:55], v[46:47], v[14:15], v[38:39]
	v_pk_mul_f32 v[56:57], v[48:49], v[16:17]
	v_pk_mul_f32 v[58:59], v[50:51], v[16:17]
	v_pk_mul_f32 v[60:61], v[52:53], v[16:17]
	v_pk_mul_f32 v[62:63], v[54:55], v[16:17]
	v_exp_f32_e32 v56, v56
	v_exp_f32_e32 v57, v57
	v_exp_f32_e32 v58, v58
	v_exp_f32_e32 v59, v59
	v_exp_f32_e32 v60, v60
	v_exp_f32_e32 v61, v61
	v_exp_f32_e32 v62, v62
	v_exp_f32_e32 v63, v63
	s_nop 0
	v_pk_add_f32 v[56:57], v[56:57], v[24:25]
	v_pk_add_f32 v[58:59], v[58:59], v[24:25]
	v_pk_add_f32 v[60:61], v[60:61], v[24:25]
	v_pk_add_f32 v[62:63], v[62:63], v[24:25]
	v_rcp_f32_e32 v56, v56
	v_rcp_f32_e32 v57, v57
	v_rcp_f32_e32 v58, v58
	v_rcp_f32_e32 v59, v59
	v_rcp_f32_e32 v60, v60
	v_rcp_f32_e32 v61, v61
	v_rcp_f32_e32 v62, v62
	v_rcp_f32_e32 v63, v63
	s_nop 0
	v_pk_fma_f32 v[56:57], v[56:57], v[20:21], v[18:19]
	v_pk_fma_f32 v[58:59], v[58:59], v[20:21], v[18:19]
	v_pk_fma_f32 v[60:61], v[60:61], v[20:21], v[18:19]
	v_pk_fma_f32 v[62:63], v[62:63], v[20:21], v[18:19]
	v_pk_fma_f32 v[56:57], v[48:49], v[22:23], v[56:57]
	v_pk_fma_f32 v[58:59], v[50:51], v[22:23], v[58:59]
	v_pk_fma_f32 v[60:61], v[52:53], v[22:23], v[60:61]
	v_pk_fma_f32 v[62:63], v[54:55], v[22:23], v[62:63]
	v_cvt_pk_bf16_f32 v64, v56, v57
	v_cvt_pk_bf16_f32 v65, v58, v59
	v_cvt_pk_bf16_f32 v66, v60, v61
	v_cvt_pk_bf16_f32 v67, v62, v63
	global_store_dwordx4 v3, v[64:67], s[12:13]
	s_add_u32 s12, s12, 0x400
	s_addc_u32 s13, s13, 0
	s_waitcnt vmcnt(21)
	v_lshlrev_b32_e32 v32, 16, v172
	v_and_b32_e32 v33, 0xffff0000, v172
	v_lshlrev_b32_e32 v34, 16, v173
	v_and_b32_e32 v35, 0xffff0000, v173
	v_lshlrev_b32_e32 v36, 16, v174
	v_and_b32_e32 v37, 0xffff0000, v174
	v_lshlrev_b32_e32 v38, 16, v175
	v_and_b32_e32 v39, 0xffff0000, v175
	v_lshlrev_b32_e32 v40, 16, v176
	v_and_b32_e32 v41, 0xffff0000, v176
	v_lshlrev_b32_e32 v42, 16, v177
	v_and_b32_e32 v43, 0xffff0000, v177
	v_lshlrev_b32_e32 v44, 16, v178
	v_and_b32_e32 v45, 0xffff0000, v178
	v_lshlrev_b32_e32 v46, 16, v179
	v_and_b32_e32 v47, 0xffff0000, v179
	v_pk_add_f32 v[40:41], v[40:41], v[32:33] neg_lo:[0,1] neg_hi:[0,1]
	v_pk_add_f32 v[42:43], v[42:43], v[34:35] neg_lo:[0,1] neg_hi:[0,1]
	v_pk_add_f32 v[44:45], v[44:45], v[36:37] neg_lo:[0,1] neg_hi:[0,1]
	v_pk_add_f32 v[46:47], v[46:47], v[38:39] neg_lo:[0,1] neg_hi:[0,1]
	v_pk_fma_f32 v[48:49], v[40:41], v[8:9], v[32:33]
	v_pk_fma_f32 v[50:51], v[42:43], v[10:11], v[34:35]
	v_pk_fma_f32 v[52:53], v[44:45], v[12:13], v[36:37]
	v_pk_fma_f32 v[54:55], v[46:47], v[14:15], v[38:39]
	v_pk_mul_f32 v[56:57], v[48:49], v[16:17]
	v_pk_mul_f32 v[58:59], v[50:51], v[16:17]
	v_pk_mul_f32 v[60:61], v[52:53], v[16:17]
	v_pk_mul_f32 v[62:63], v[54:55], v[16:17]
	v_exp_f32_e32 v56, v56
	v_exp_f32_e32 v57, v57
	v_exp_f32_e32 v58, v58
	v_exp_f32_e32 v59, v59
	v_exp_f32_e32 v60, v60
	v_exp_f32_e32 v61, v61
	v_exp_f32_e32 v62, v62
	v_exp_f32_e32 v63, v63
	s_nop 0
	v_pk_add_f32 v[56:57], v[56:57], v[24:25]
	v_pk_add_f32 v[58:59], v[58:59], v[24:25]
	v_pk_add_f32 v[60:61], v[60:61], v[24:25]
	v_pk_add_f32 v[62:63], v[62:63], v[24:25]
	v_rcp_f32_e32 v56, v56
	v_rcp_f32_e32 v57, v57
	v_rcp_f32_e32 v58, v58
	v_rcp_f32_e32 v59, v59
	v_rcp_f32_e32 v60, v60
	v_rcp_f32_e32 v61, v61
	v_rcp_f32_e32 v62, v62
	v_rcp_f32_e32 v63, v63
	s_nop 0
	v_pk_fma_f32 v[56:57], v[56:57], v[20:21], v[18:19]
	v_pk_fma_f32 v[58:59], v[58:59], v[20:21], v[18:19]
	v_pk_fma_f32 v[60:61], v[60:61], v[20:21], v[18:19]
	v_pk_fma_f32 v[62:63], v[62:63], v[20:21], v[18:19]
	v_pk_fma_f32 v[56:57], v[48:49], v[22:23], v[56:57]
	v_pk_fma_f32 v[58:59], v[50:51], v[22:23], v[58:59]
	v_pk_fma_f32 v[60:61], v[52:53], v[22:23], v[60:61]
	v_pk_fma_f32 v[62:63], v[54:55], v[22:23], v[62:63]
	v_cvt_pk_bf16_f32 v64, v56, v57
	v_cvt_pk_bf16_f32 v65, v58, v59
	v_cvt_pk_bf16_f32 v66, v60, v61
	v_cvt_pk_bf16_f32 v67, v62, v63
	global_store_dwordx4 v3, v[64:67], s[12:13]
	s_add_u32 s12, s12, 0x400
	s_addc_u32 s13, s13, 0
	s_waitcnt vmcnt(20)
	v_lshlrev_b32_e32 v32, 16, v180
	v_and_b32_e32 v33, 0xffff0000, v180
	v_lshlrev_b32_e32 v34, 16, v181
	v_and_b32_e32 v35, 0xffff0000, v181
	v_lshlrev_b32_e32 v36, 16, v182
	v_and_b32_e32 v37, 0xffff0000, v182
	v_lshlrev_b32_e32 v38, 16, v183
	v_and_b32_e32 v39, 0xffff0000, v183
	v_lshlrev_b32_e32 v40, 16, v184
	v_and_b32_e32 v41, 0xffff0000, v184
	v_lshlrev_b32_e32 v42, 16, v185
	v_and_b32_e32 v43, 0xffff0000, v185
	v_lshlrev_b32_e32 v44, 16, v186
	v_and_b32_e32 v45, 0xffff0000, v186
	v_lshlrev_b32_e32 v46, 16, v187
	v_and_b32_e32 v47, 0xffff0000, v187
	v_pk_add_f32 v[40:41], v[40:41], v[32:33] neg_lo:[0,1] neg_hi:[0,1]
	v_pk_add_f32 v[42:43], v[42:43], v[34:35] neg_lo:[0,1] neg_hi:[0,1]
	v_pk_add_f32 v[44:45], v[44:45], v[36:37] neg_lo:[0,1] neg_hi:[0,1]
	v_pk_add_f32 v[46:47], v[46:47], v[38:39] neg_lo:[0,1] neg_hi:[0,1]
	v_pk_fma_f32 v[48:49], v[40:41], v[8:9], v[32:33]
	v_pk_fma_f32 v[50:51], v[42:43], v[10:11], v[34:35]
	v_pk_fma_f32 v[52:53], v[44:45], v[12:13], v[36:37]
	v_pk_fma_f32 v[54:55], v[46:47], v[14:15], v[38:39]
	v_pk_mul_f32 v[56:57], v[48:49], v[16:17]
	v_pk_mul_f32 v[58:59], v[50:51], v[16:17]
	v_pk_mul_f32 v[60:61], v[52:53], v[16:17]
	v_pk_mul_f32 v[62:63], v[54:55], v[16:17]
	v_exp_f32_e32 v56, v56
	v_exp_f32_e32 v57, v57
	v_exp_f32_e32 v58, v58
	v_exp_f32_e32 v59, v59
	v_exp_f32_e32 v60, v60
	v_exp_f32_e32 v61, v61
	v_exp_f32_e32 v62, v62
	v_exp_f32_e32 v63, v63
	s_nop 0
	v_pk_add_f32 v[56:57], v[56:57], v[24:25]
	v_pk_add_f32 v[58:59], v[58:59], v[24:25]
	v_pk_add_f32 v[60:61], v[60:61], v[24:25]
	v_pk_add_f32 v[62:63], v[62:63], v[24:25]
	v_rcp_f32_e32 v56, v56
	v_rcp_f32_e32 v57, v57
	v_rcp_f32_e32 v58, v58
	v_rcp_f32_e32 v59, v59
	v_rcp_f32_e32 v60, v60
	v_rcp_f32_e32 v61, v61
	v_rcp_f32_e32 v62, v62
	v_rcp_f32_e32 v63, v63
	s_nop 0
	v_pk_fma_f32 v[56:57], v[56:57], v[20:21], v[18:19]
	v_pk_fma_f32 v[58:59], v[58:59], v[20:21], v[18:19]
	v_pk_fma_f32 v[60:61], v[60:61], v[20:21], v[18:19]
	v_pk_fma_f32 v[62:63], v[62:63], v[20:21], v[18:19]
	v_pk_fma_f32 v[56:57], v[48:49], v[22:23], v[56:57]
	v_pk_fma_f32 v[58:59], v[50:51], v[22:23], v[58:59]
	v_pk_fma_f32 v[60:61], v[52:53], v[22:23], v[60:61]
	v_pk_fma_f32 v[62:63], v[54:55], v[22:23], v[62:63]
	v_cvt_pk_bf16_f32 v64, v56, v57
	v_cvt_pk_bf16_f32 v65, v58, v59
	v_cvt_pk_bf16_f32 v66, v60, v61
	v_cvt_pk_bf16_f32 v67, v62, v63
	global_store_dwordx4 v3, v[64:67], s[12:13]
	s_add_u32 s12, s12, 0x400
	s_addc_u32 s13, s13, 0
	s_waitcnt vmcnt(19)
	v_lshlrev_b32_e32 v32, 16, v188
	v_and_b32_e32 v33, 0xffff0000, v188
	v_lshlrev_b32_e32 v34, 16, v189
	v_and_b32_e32 v35, 0xffff0000, v189
	v_lshlrev_b32_e32 v36, 16, v190
	v_and_b32_e32 v37, 0xffff0000, v190
	v_lshlrev_b32_e32 v38, 16, v191
	v_and_b32_e32 v39, 0xffff0000, v191
	v_lshlrev_b32_e32 v40, 16, v192
	v_and_b32_e32 v41, 0xffff0000, v192
	v_lshlrev_b32_e32 v42, 16, v193
	v_and_b32_e32 v43, 0xffff0000, v193
	v_lshlrev_b32_e32 v44, 16, v194
	v_and_b32_e32 v45, 0xffff0000, v194
	v_lshlrev_b32_e32 v46, 16, v195
	v_and_b32_e32 v47, 0xffff0000, v195
	v_pk_add_f32 v[40:41], v[40:41], v[32:33] neg_lo:[0,1] neg_hi:[0,1]
	v_pk_add_f32 v[42:43], v[42:43], v[34:35] neg_lo:[0,1] neg_hi:[0,1]
	v_pk_add_f32 v[44:45], v[44:45], v[36:37] neg_lo:[0,1] neg_hi:[0,1]
	v_pk_add_f32 v[46:47], v[46:47], v[38:39] neg_lo:[0,1] neg_hi:[0,1]
	v_pk_fma_f32 v[48:49], v[40:41], v[8:9], v[32:33]
	v_pk_fma_f32 v[50:51], v[42:43], v[10:11], v[34:35]
	v_pk_fma_f32 v[52:53], v[44:45], v[12:13], v[36:37]
	v_pk_fma_f32 v[54:55], v[46:47], v[14:15], v[38:39]
	v_pk_mul_f32 v[56:57], v[48:49], v[16:17]
	v_pk_mul_f32 v[58:59], v[50:51], v[16:17]
	v_pk_mul_f32 v[60:61], v[52:53], v[16:17]
	v_pk_mul_f32 v[62:63], v[54:55], v[16:17]
	v_exp_f32_e32 v56, v56
	v_exp_f32_e32 v57, v57
	v_exp_f32_e32 v58, v58
	v_exp_f32_e32 v59, v59
	v_exp_f32_e32 v60, v60
	v_exp_f32_e32 v61, v61
	v_exp_f32_e32 v62, v62
	v_exp_f32_e32 v63, v63
	s_nop 0
	v_pk_add_f32 v[56:57], v[56:57], v[24:25]
	v_pk_add_f32 v[58:59], v[58:59], v[24:25]
	v_pk_add_f32 v[60:61], v[60:61], v[24:25]
	v_pk_add_f32 v[62:63], v[62:63], v[24:25]
	v_rcp_f32_e32 v56, v56
	v_rcp_f32_e32 v57, v57
	v_rcp_f32_e32 v58, v58
	v_rcp_f32_e32 v59, v59
	v_rcp_f32_e32 v60, v60
	v_rcp_f32_e32 v61, v61
	v_rcp_f32_e32 v62, v62
	v_rcp_f32_e32 v63, v63
	s_nop 0
	v_pk_fma_f32 v[56:57], v[56:57], v[20:21], v[18:19]
	v_pk_fma_f32 v[58:59], v[58:59], v[20:21], v[18:19]
	v_pk_fma_f32 v[60:61], v[60:61], v[20:21], v[18:19]
	v_pk_fma_f32 v[62:63], v[62:63], v[20:21], v[18:19]
	v_pk_fma_f32 v[56:57], v[48:49], v[22:23], v[56:57]
	v_pk_fma_f32 v[58:59], v[50:51], v[22:23], v[58:59]
	v_pk_fma_f32 v[60:61], v[52:53], v[22:23], v[60:61]
	v_pk_fma_f32 v[62:63], v[54:55], v[22:23], v[62:63]
	v_cvt_pk_bf16_f32 v64, v56, v57
	v_cvt_pk_bf16_f32 v65, v58, v59
	v_cvt_pk_bf16_f32 v66, v60, v61
	v_cvt_pk_bf16_f32 v67, v62, v63
	global_store_dwordx4 v3, v[64:67], s[12:13]
	s_add_u32 s12, s12, 0x400
	s_addc_u32 s13, s13, 0
	s_waitcnt vmcnt(18)
	v_lshlrev_b32_e32 v32, 16, v196
	v_and_b32_e32 v33, 0xffff0000, v196
	v_lshlrev_b32_e32 v34, 16, v197
	v_and_b32_e32 v35, 0xffff0000, v197
	v_lshlrev_b32_e32 v36, 16, v198
	v_and_b32_e32 v37, 0xffff0000, v198
	v_lshlrev_b32_e32 v38, 16, v199
	v_and_b32_e32 v39, 0xffff0000, v199
	v_lshlrev_b32_e32 v40, 16, v200
	v_and_b32_e32 v41, 0xffff0000, v200
	v_lshlrev_b32_e32 v42, 16, v201
	v_and_b32_e32 v43, 0xffff0000, v201
	v_lshlrev_b32_e32 v44, 16, v202
	v_and_b32_e32 v45, 0xffff0000, v202
	v_lshlrev_b32_e32 v46, 16, v203
	v_and_b32_e32 v47, 0xffff0000, v203
	v_pk_add_f32 v[40:41], v[40:41], v[32:33] neg_lo:[0,1] neg_hi:[0,1]
	v_pk_add_f32 v[42:43], v[42:43], v[34:35] neg_lo:[0,1] neg_hi:[0,1]
	v_pk_add_f32 v[44:45], v[44:45], v[36:37] neg_lo:[0,1] neg_hi:[0,1]
	v_pk_add_f32 v[46:47], v[46:47], v[38:39] neg_lo:[0,1] neg_hi:[0,1]
	v_pk_fma_f32 v[48:49], v[40:41], v[8:9], v[32:33]
	v_pk_fma_f32 v[50:51], v[42:43], v[10:11], v[34:35]
	v_pk_fma_f32 v[52:53], v[44:45], v[12:13], v[36:37]
	v_pk_fma_f32 v[54:55], v[46:47], v[14:15], v[38:39]
	v_pk_mul_f32 v[56:57], v[48:49], v[16:17]
	v_pk_mul_f32 v[58:59], v[50:51], v[16:17]
	v_pk_mul_f32 v[60:61], v[52:53], v[16:17]
	v_pk_mul_f32 v[62:63], v[54:55], v[16:17]
	v_exp_f32_e32 v56, v56
	v_exp_f32_e32 v57, v57
	v_exp_f32_e32 v58, v58
	v_exp_f32_e32 v59, v59
	v_exp_f32_e32 v60, v60
	v_exp_f32_e32 v61, v61
	v_exp_f32_e32 v62, v62
	v_exp_f32_e32 v63, v63
	s_nop 0
	v_pk_add_f32 v[56:57], v[56:57], v[24:25]
	v_pk_add_f32 v[58:59], v[58:59], v[24:25]
	v_pk_add_f32 v[60:61], v[60:61], v[24:25]
	v_pk_add_f32 v[62:63], v[62:63], v[24:25]
	v_rcp_f32_e32 v56, v56
	v_rcp_f32_e32 v57, v57
	v_rcp_f32_e32 v58, v58
	v_rcp_f32_e32 v59, v59
	v_rcp_f32_e32 v60, v60
	v_rcp_f32_e32 v61, v61
	v_rcp_f32_e32 v62, v62
	v_rcp_f32_e32 v63, v63
	s_nop 0
	v_pk_fma_f32 v[56:57], v[56:57], v[20:21], v[18:19]
	v_pk_fma_f32 v[58:59], v[58:59], v[20:21], v[18:19]
	v_pk_fma_f32 v[60:61], v[60:61], v[20:21], v[18:19]
	v_pk_fma_f32 v[62:63], v[62:63], v[20:21], v[18:19]
	v_pk_fma_f32 v[56:57], v[48:49], v[22:23], v[56:57]
	v_pk_fma_f32 v[58:59], v[50:51], v[22:23], v[58:59]
	v_pk_fma_f32 v[60:61], v[52:53], v[22:23], v[60:61]
	v_pk_fma_f32 v[62:63], v[54:55], v[22:23], v[62:63]
	v_cvt_pk_bf16_f32 v64, v56, v57
	v_cvt_pk_bf16_f32 v65, v58, v59
	v_cvt_pk_bf16_f32 v66, v60, v61
	v_cvt_pk_bf16_f32 v67, v62, v63
	global_store_dwordx4 v3, v[64:67], s[12:13]
	s_add_u32 s12, s12, 0x400
	s_addc_u32 s13, s13, 0
	s_waitcnt vmcnt(17)
	v_lshlrev_b32_e32 v32, 16, v204
	v_and_b32_e32 v33, 0xffff0000, v204
	v_lshlrev_b32_e32 v34, 16, v205
	v_and_b32_e32 v35, 0xffff0000, v205
	v_lshlrev_b32_e32 v36, 16, v206
	v_and_b32_e32 v37, 0xffff0000, v206
	v_lshlrev_b32_e32 v38, 16, v207
	v_and_b32_e32 v39, 0xffff0000, v207
	v_lshlrev_b32_e32 v40, 16, v208
	v_and_b32_e32 v41, 0xffff0000, v208
	v_lshlrev_b32_e32 v42, 16, v209
	v_and_b32_e32 v43, 0xffff0000, v209
	v_lshlrev_b32_e32 v44, 16, v210
	v_and_b32_e32 v45, 0xffff0000, v210
	v_lshlrev_b32_e32 v46, 16, v211
	v_and_b32_e32 v47, 0xffff0000, v211
	v_pk_add_f32 v[40:41], v[40:41], v[32:33] neg_lo:[0,1] neg_hi:[0,1]
	v_pk_add_f32 v[42:43], v[42:43], v[34:35] neg_lo:[0,1] neg_hi:[0,1]
	v_pk_add_f32 v[44:45], v[44:45], v[36:37] neg_lo:[0,1] neg_hi:[0,1]
	v_pk_add_f32 v[46:47], v[46:47], v[38:39] neg_lo:[0,1] neg_hi:[0,1]
	v_pk_fma_f32 v[48:49], v[40:41], v[8:9], v[32:33]
	v_pk_fma_f32 v[50:51], v[42:43], v[10:11], v[34:35]
	v_pk_fma_f32 v[52:53], v[44:45], v[12:13], v[36:37]
	v_pk_fma_f32 v[54:55], v[46:47], v[14:15], v[38:39]
	v_pk_mul_f32 v[56:57], v[48:49], v[16:17]
	v_pk_mul_f32 v[58:59], v[50:51], v[16:17]
	v_pk_mul_f32 v[60:61], v[52:53], v[16:17]
	v_pk_mul_f32 v[62:63], v[54:55], v[16:17]
	v_exp_f32_e32 v56, v56
	v_exp_f32_e32 v57, v57
	v_exp_f32_e32 v58, v58
	v_exp_f32_e32 v59, v59
	v_exp_f32_e32 v60, v60
	v_exp_f32_e32 v61, v61
	v_exp_f32_e32 v62, v62
	v_exp_f32_e32 v63, v63
	s_nop 0
	v_pk_add_f32 v[56:57], v[56:57], v[24:25]
	v_pk_add_f32 v[58:59], v[58:59], v[24:25]
	v_pk_add_f32 v[60:61], v[60:61], v[24:25]
	v_pk_add_f32 v[62:63], v[62:63], v[24:25]
	v_rcp_f32_e32 v56, v56
	v_rcp_f32_e32 v57, v57
	v_rcp_f32_e32 v58, v58
	v_rcp_f32_e32 v59, v59
	v_rcp_f32_e32 v60, v60
	v_rcp_f32_e32 v61, v61
	v_rcp_f32_e32 v62, v62
	v_rcp_f32_e32 v63, v63
	s_nop 0
	v_pk_fma_f32 v[56:57], v[56:57], v[20:21], v[18:19]
	v_pk_fma_f32 v[58:59], v[58:59], v[20:21], v[18:19]
	v_pk_fma_f32 v[60:61], v[60:61], v[20:21], v[18:19]
	v_pk_fma_f32 v[62:63], v[62:63], v[20:21], v[18:19]
	v_pk_fma_f32 v[56:57], v[48:49], v[22:23], v[56:57]
	v_pk_fma_f32 v[58:59], v[50:51], v[22:23], v[58:59]
	v_pk_fma_f32 v[60:61], v[52:53], v[22:23], v[60:61]
	v_pk_fma_f32 v[62:63], v[54:55], v[22:23], v[62:63]
	v_cvt_pk_bf16_f32 v64, v56, v57
	v_cvt_pk_bf16_f32 v65, v58, v59
	v_cvt_pk_bf16_f32 v66, v60, v61
	v_cvt_pk_bf16_f32 v67, v62, v63
	global_store_dwordx4 v3, v[64:67], s[12:13]
	s_add_u32 s12, s12, 0x400
	s_addc_u32 s13, s13, 0
	s_waitcnt vmcnt(16)
	v_lshlrev_b32_e32 v32, 16, v212
	v_and_b32_e32 v33, 0xffff0000, v212
	v_lshlrev_b32_e32 v34, 16, v213
	v_and_b32_e32 v35, 0xffff0000, v213
	v_lshlrev_b32_e32 v36, 16, v214
	v_and_b32_e32 v37, 0xffff0000, v214
	v_lshlrev_b32_e32 v38, 16, v215
	v_and_b32_e32 v39, 0xffff0000, v215
	v_lshlrev_b32_e32 v40, 16, v216
	v_and_b32_e32 v41, 0xffff0000, v216
	v_lshlrev_b32_e32 v42, 16, v217
	v_and_b32_e32 v43, 0xffff0000, v217
	v_lshlrev_b32_e32 v44, 16, v218
	v_and_b32_e32 v45, 0xffff0000, v218
	v_lshlrev_b32_e32 v46, 16, v219
	v_and_b32_e32 v47, 0xffff0000, v219
	v_pk_add_f32 v[40:41], v[40:41], v[32:33] neg_lo:[0,1] neg_hi:[0,1]
	v_pk_add_f32 v[42:43], v[42:43], v[34:35] neg_lo:[0,1] neg_hi:[0,1]
	v_pk_add_f32 v[44:45], v[44:45], v[36:37] neg_lo:[0,1] neg_hi:[0,1]
	v_pk_add_f32 v[46:47], v[46:47], v[38:39] neg_lo:[0,1] neg_hi:[0,1]
	v_pk_fma_f32 v[48:49], v[40:41], v[8:9], v[32:33]
	v_pk_fma_f32 v[50:51], v[42:43], v[10:11], v[34:35]
	v_pk_fma_f32 v[52:53], v[44:45], v[12:13], v[36:37]
	v_pk_fma_f32 v[54:55], v[46:47], v[14:15], v[38:39]
	v_pk_mul_f32 v[56:57], v[48:49], v[16:17]
	v_pk_mul_f32 v[58:59], v[50:51], v[16:17]
	v_pk_mul_f32 v[60:61], v[52:53], v[16:17]
	v_pk_mul_f32 v[62:63], v[54:55], v[16:17]
	v_exp_f32_e32 v56, v56
	v_exp_f32_e32 v57, v57
	v_exp_f32_e32 v58, v58
	v_exp_f32_e32 v59, v59
	v_exp_f32_e32 v60, v60
	v_exp_f32_e32 v61, v61
	v_exp_f32_e32 v62, v62
	v_exp_f32_e32 v63, v63
	s_nop 0
	v_pk_add_f32 v[56:57], v[56:57], v[24:25]
	v_pk_add_f32 v[58:59], v[58:59], v[24:25]
	v_pk_add_f32 v[60:61], v[60:61], v[24:25]
	v_pk_add_f32 v[62:63], v[62:63], v[24:25]
	v_rcp_f32_e32 v56, v56
	v_rcp_f32_e32 v57, v57
	v_rcp_f32_e32 v58, v58
	v_rcp_f32_e32 v59, v59
	v_rcp_f32_e32 v60, v60
	v_rcp_f32_e32 v61, v61
	v_rcp_f32_e32 v62, v62
	v_rcp_f32_e32 v63, v63
	s_nop 0
	v_pk_fma_f32 v[56:57], v[56:57], v[20:21], v[18:19]
	v_pk_fma_f32 v[58:59], v[58:59], v[20:21], v[18:19]
	v_pk_fma_f32 v[60:61], v[60:61], v[20:21], v[18:19]
	v_pk_fma_f32 v[62:63], v[62:63], v[20:21], v[18:19]
	v_pk_fma_f32 v[56:57], v[48:49], v[22:23], v[56:57]
	v_pk_fma_f32 v[58:59], v[50:51], v[22:23], v[58:59]
	v_pk_fma_f32 v[60:61], v[52:53], v[22:23], v[60:61]
	v_pk_fma_f32 v[62:63], v[54:55], v[22:23], v[62:63]
	v_cvt_pk_bf16_f32 v64, v56, v57
	v_cvt_pk_bf16_f32 v65, v58, v59
	v_cvt_pk_bf16_f32 v66, v60, v61
	v_cvt_pk_bf16_f32 v67, v62, v63
	global_store_dwordx4 v3, v[64:67], s[12:13]
	s_add_u32 s12, s12, 0x400
	s_addc_u32 s13, s13, 0
	s_waitcnt vmcnt(15)
	v_lshlrev_b32_e32 v32, 16, v220
	v_and_b32_e32 v33, 0xffff0000, v220
	v_lshlrev_b32_e32 v34, 16, v221
	v_and_b32_e32 v35, 0xffff0000, v221
	v_lshlrev_b32_e32 v36, 16, v222
	v_and_b32_e32 v37, 0xffff0000, v222
	v_lshlrev_b32_e32 v38, 16, v223
	v_and_b32_e32 v39, 0xffff0000, v223
	v_lshlrev_b32_e32 v40, 16, v224
	v_and_b32_e32 v41, 0xffff0000, v224
	v_lshlrev_b32_e32 v42, 16, v225
	v_and_b32_e32 v43, 0xffff0000, v225
	v_lshlrev_b32_e32 v44, 16, v226
	v_and_b32_e32 v45, 0xffff0000, v226
	v_lshlrev_b32_e32 v46, 16, v227
	v_and_b32_e32 v47, 0xffff0000, v227
	v_pk_add_f32 v[40:41], v[40:41], v[32:33] neg_lo:[0,1] neg_hi:[0,1]
	v_pk_add_f32 v[42:43], v[42:43], v[34:35] neg_lo:[0,1] neg_hi:[0,1]
	v_pk_add_f32 v[44:45], v[44:45], v[36:37] neg_lo:[0,1] neg_hi:[0,1]
	v_pk_add_f32 v[46:47], v[46:47], v[38:39] neg_lo:[0,1] neg_hi:[0,1]
	v_pk_fma_f32 v[48:49], v[40:41], v[8:9], v[32:33]
	v_pk_fma_f32 v[50:51], v[42:43], v[10:11], v[34:35]
	v_pk_fma_f32 v[52:53], v[44:45], v[12:13], v[36:37]
	v_pk_fma_f32 v[54:55], v[46:47], v[14:15], v[38:39]
	v_pk_mul_f32 v[56:57], v[48:49], v[16:17]
	v_pk_mul_f32 v[58:59], v[50:51], v[16:17]
	v_pk_mul_f32 v[60:61], v[52:53], v[16:17]
	v_pk_mul_f32 v[62:63], v[54:55], v[16:17]
	v_exp_f32_e32 v56, v56
	v_exp_f32_e32 v57, v57
	v_exp_f32_e32 v58, v58
	v_exp_f32_e32 v59, v59
	v_exp_f32_e32 v60, v60
	v_exp_f32_e32 v61, v61
	v_exp_f32_e32 v62, v62
	v_exp_f32_e32 v63, v63
	s_nop 0
	v_pk_add_f32 v[56:57], v[56:57], v[24:25]
	v_pk_add_f32 v[58:59], v[58:59], v[24:25]
	v_pk_add_f32 v[60:61], v[60:61], v[24:25]
	v_pk_add_f32 v[62:63], v[62:63], v[24:25]
	v_rcp_f32_e32 v56, v56
	v_rcp_f32_e32 v57, v57
	v_rcp_f32_e32 v58, v58
	v_rcp_f32_e32 v59, v59
	v_rcp_f32_e32 v60, v60
	v_rcp_f32_e32 v61, v61
	v_rcp_f32_e32 v62, v62
	v_rcp_f32_e32 v63, v63
	s_nop 0
	v_pk_fma_f32 v[56:57], v[56:57], v[20:21], v[18:19]
	v_pk_fma_f32 v[58:59], v[58:59], v[20:21], v[18:19]
	v_pk_fma_f32 v[60:61], v[60:61], v[20:21], v[18:19]
	v_pk_fma_f32 v[62:63], v[62:63], v[20:21], v[18:19]
	v_pk_fma_f32 v[56:57], v[48:49], v[22:23], v[56:57]
	v_pk_fma_f32 v[58:59], v[50:51], v[22:23], v[58:59]
	v_pk_fma_f32 v[60:61], v[52:53], v[22:23], v[60:61]
	v_pk_fma_f32 v[62:63], v[54:55], v[22:23], v[62:63]
	v_cvt_pk_bf16_f32 v64, v56, v57
	v_cvt_pk_bf16_f32 v65, v58, v59
	v_cvt_pk_bf16_f32 v66, v60, v61
	v_cvt_pk_bf16_f32 v67, v62, v63
	global_store_dwordx4 v3, v[64:67], s[12:13]
	s_add_u32 s12, s12, 0x400
	s_addc_u32 s13, s13, 0
	s_mov_b64 s[38:39], exec
	s_branch .LBB0_669
.Lp2a_compiled:
	s_and_saveexec_b64 s[38:39], vcc
	s_cbranch_execz .LBB0_669
	v_and_b32_e32 v8, 0xf8, v56
	v_lshlrev_b32_e32 v42, 2, v8
	v_mov_b32_e32 v43, 0
	v_lshl_add_u64 v[0:1], s[46:47], 0, v[42:43]
	s_mov_b64 s[0:1], 0x1800
	v_lshl_add_u64 v[4:5], v[0:1], 0, s[0:1]
	v_add_co_u32_e32 v0, vcc, 0x1000, v0
	s_movk_i32 s0, 0x80
	s_nop 0
	v_addc_co_u32_e32 v1, vcc, 0, v1, vcc
	global_load_dwordx4 v[0:3], v[0:1], off offset:2048
	s_nop 0
	global_load_dwordx4 v[4:7], v[4:5], off offset:16
	v_lshlrev_b32_e32 v42, 1, v8
	v_cmp_lt_u32_e32 vcc, 63, v8
	v_cmp_gt_u32_e64 s[0:1], s0, v8
	v_lshl_add_u64 v[8:9], s[96:97], 0, v[42:43]
	s_mov_b64 s[4:5], 0x25800000
	v_lshl_add_u64 v[46:47], v[8:9], 0, s[4:5]
	s_mov_b64 s[4:5], 0xf800000
	v_lshl_add_u64 v[48:49], v[8:9], 0, s[4:5]
	s_lshl_b64 s[40:41], s[20:21], 14
	s_lshl_b64 s[42:43], s[20:21], 10
	s_lshl_b64 s[50:51], s[20:21], 13
	s_lshl_b64 s[4:5], s[2:3], 12
	s_lshl_b64 s[6:7], s[22:23], 3
	s_add_u32 s4, s6, s4
	s_addc_u32 s5, s7, s5
	v_lshlrev_b64 v[50:51], 3, v[44:45]
	v_lshl_add_u64 v[52:53], v[40:41], 3, s[4:5]
	s_lshl_b64 s[54:55], s[20:21], 12
	s_mov_b64 s[56:57], 0
	s_movk_i32 s51, 0xe00
	v_mov_b64_e32 v[8:9], v[44:45]
	s_branch .LBB0_536
